# scan loader adaLN waves: next chunk w_ada row loads issued right after the FMAs; their redundant row-prefetch waits skipped
# baseline (speedup 1.0000x reference)
.LBB0_583:
	s_and_b64 vcc, exec, s[36:37]
	s_cbranch_vccnz .LBB0_585
	s_add_u32 s8, s5, s38
	s_addc_u32 s9, s41, s39
	global_load_dwordx4 v[84:87], v0, s[8:9] offset:48
	global_load_dwordx4 v[88:91], v0, s[8:9] offset:32
	s_add_u32 s6, s8, 0x2020
	s_addc_u32 s7, s9, 0
	s_waitcnt vmcnt(0)
	v_pk_fma_f32 v[230:231], v[6:7], v[88:89], v[50:51] op_sel_hi:[1,0,1]
	v_pk_fma_f32 v[232:233], v[4:5], v[88:89], v[48:49] op_sel_hi:[1,0,1]
	global_load_dwordx4 v[80:83], v0, s[6:7] offset:16
	global_load_dwordx4 v[48:51], v210, s[8:9] offset:32
	s_add_u32 s6, s8, 0x4020
	s_addc_u32 s7, s9, 0
	v_pk_fma_f32 v[230:231], v[10:11], v[88:89], v[230:231] op_sel:[0,1,0]
	v_pk_fma_f32 v[88:89], v[8:9], v[88:89], v[232:233] op_sel:[0,1,0]
	s_waitcnt vmcnt(0)
	v_pk_fma_f32 v[234:235], v[6:7], v[48:49], v[54:55] op_sel_hi:[1,0,1]
	v_pk_fma_f32 v[236:237], v[4:5], v[48:49], v[52:53] op_sel_hi:[1,0,1]
	global_load_dwordx4 v[76:79], v0, s[6:7] offset:16
	global_load_dwordx4 v[52:55], v211, s[8:9] offset:32
	s_add_u32 s6, s8, 0x6020
	s_addc_u32 s7, s9, 0
	v_pk_fma_f32 v[232:233], v[10:11], v[48:49], v[234:235] op_sel:[0,1,0]
	v_pk_fma_f32 v[48:49], v[8:9], v[48:49], v[236:237] op_sel:[0,1,0]
	v_pk_fma_f32 v[88:89], v[12:13], v[90:91], v[88:89] op_sel_hi:[1,0,1]
	v_pk_fma_f32 v[48:49], v[12:13], v[50:51], v[48:49] op_sel_hi:[1,0,1]
	s_waitcnt vmcnt(0)
	v_pk_fma_f32 v[238:239], v[6:7], v[52:53], v[58:59] op_sel_hi:[1,0,1]
	v_pk_fma_f32 v[240:241], v[4:5], v[52:53], v[56:57] op_sel_hi:[1,0,1]
	global_load_dwordx4 v[72:75], v0, s[6:7] offset:16
	global_load_dwordx4 v[56:59], v212, s[8:9] offset:32
	v_pk_fma_f32 v[234:235], v[10:11], v[52:53], v[238:239] op_sel:[0,1,0]
	v_pk_fma_f32 v[52:53], v[8:9], v[52:53], v[240:241] op_sel:[0,1,0]
	s_waitcnt vmcnt(0)
	v_pk_fma_f32 v[62:63], v[6:7], v[56:57], v[62:63] op_sel_hi:[1,0,1]
	v_pk_fma_f32 v[60:61], v[4:5], v[56:57], v[60:61] op_sel_hi:[1,0,1]
	v_pk_fma_f32 v[62:63], v[10:11], v[56:57], v[62:63] op_sel:[0,1,0]
	v_pk_fma_f32 v[56:57], v[8:9], v[56:57], v[60:61] op_sel:[0,1,0]
	v_pk_fma_f32 v[60:61], v[14:15], v[90:91], v[230:231] op_sel_hi:[1,0,1]
	v_pk_fma_f32 v[230:231], v[14:15], v[50:51], v[232:233] op_sel_hi:[1,0,1]
	v_mov_b32_e32 v50, v91
	v_pk_fma_f32 v[60:61], v[18:19], v[50:51], v[60:61] op_sel_hi:[1,0,1]
	v_pk_fma_f32 v[88:89], v[16:17], v[50:51], v[88:89] op_sel_hi:[1,0,1]
	v_mov_b32_e32 v50, v51
	v_pk_fma_f32 v[232:233], v[14:15], v[54:55], v[234:235] op_sel_hi:[1,0,1]
	v_pk_fma_f32 v[52:53], v[12:13], v[54:55], v[52:53] op_sel_hi:[1,0,1]
	v_pk_fma_f32 v[90:91], v[18:19], v[50:51], v[230:231] op_sel_hi:[1,0,1]
	v_pk_fma_f32 v[48:49], v[16:17], v[50:51], v[48:49] op_sel_hi:[1,0,1]
	v_mov_b32_e32 v50, v55
	v_pk_fma_f32 v[62:63], v[14:15], v[58:59], v[62:63] op_sel_hi:[1,0,1]
	v_pk_fma_f32 v[56:57], v[12:13], v[58:59], v[56:57] op_sel_hi:[1,0,1]
	v_pk_fma_f32 v[54:55], v[18:19], v[50:51], v[232:233] op_sel_hi:[1,0,1]
	v_pk_fma_f32 v[50:51], v[16:17], v[50:51], v[52:53] op_sel_hi:[1,0,1]
	v_mov_b32_e32 v52, v59
	v_pk_fma_f32 v[58:59], v[18:19], v[52:53], v[62:63] op_sel_hi:[1,0,1]
	v_pk_fma_f32 v[52:53], v[16:17], v[52:53], v[56:57] op_sel_hi:[1,0,1]
	v_pk_fma_f32 v[56:57], v[22:23], v[84:85], v[60:61] op_sel_hi:[1,0,1]
	v_pk_fma_f32 v[60:61], v[20:21], v[84:85], v[88:89] op_sel_hi:[1,0,1]
	v_pk_fma_f32 v[62:63], v[22:23], v[80:81], v[90:91] op_sel_hi:[1,0,1]
	v_pk_fma_f32 v[54:55], v[22:23], v[76:77], v[54:55] op_sel_hi:[1,0,1]
	v_pk_fma_f32 v[50:51], v[20:21], v[76:77], v[50:51] op_sel_hi:[1,0,1]
	v_pk_fma_f32 v[58:59], v[22:23], v[72:73], v[58:59] op_sel_hi:[1,0,1]
	v_pk_fma_f32 v[52:53], v[20:21], v[72:73], v[52:53] op_sel_hi:[1,0,1]
	v_pk_fma_f32 v[48:49], v[20:21], v[80:81], v[48:49] op_sel_hi:[1,0,1]
	v_pk_fma_f32 v[56:57], v[26:27], v[84:85], v[56:57] op_sel:[0,1,0]
	v_pk_fma_f32 v[60:61], v[24:25], v[84:85], v[60:61] op_sel:[0,1,0]
	v_pk_fma_f32 v[62:63], v[26:27], v[80:81], v[62:63] op_sel:[0,1,0]
	v_pk_fma_f32 v[54:55], v[26:27], v[76:77], v[54:55] op_sel:[0,1,0]
	v_pk_fma_f32 v[50:51], v[24:25], v[76:77], v[50:51] op_sel:[0,1,0]
	v_pk_fma_f32 v[58:59], v[26:27], v[72:73], v[58:59] op_sel:[0,1,0]
	v_pk_fma_f32 v[52:53], v[24:25], v[72:73], v[52:53] op_sel:[0,1,0]
	v_pk_fma_f32 v[48:49], v[24:25], v[80:81], v[48:49] op_sel:[0,1,0]
	v_pk_fma_f32 v[76:77], v[30:31], v[86:87], v[56:57] op_sel_hi:[1,0,1]
	v_pk_fma_f32 v[80:81], v[28:29], v[86:87], v[60:61] op_sel_hi:[1,0,1]
	v_pk_fma_f32 v[84:85], v[30:31], v[82:83], v[62:63] op_sel_hi:[1,0,1]
	v_pk_fma_f32 v[56:57], v[30:31], v[78:79], v[54:55] op_sel_hi:[1,0,1]
	v_pk_fma_f32 v[62:63], v[28:29], v[78:79], v[50:51] op_sel_hi:[1,0,1]
	v_pk_fma_f32 v[60:61], v[30:31], v[74:75], v[58:59] op_sel_hi:[1,0,1]
	v_pk_fma_f32 v[72:73], v[28:29], v[74:75], v[52:53] op_sel_hi:[1,0,1]
	v_mov_b32_e32 v74, v79
	v_pk_fma_f32 v[88:89], v[28:29], v[82:83], v[48:49] op_sel_hi:[1,0,1]
	v_mov_b32_e32 v48, v87
	v_mov_b32_e32 v52, v83
	v_pk_fma_f32 v[58:59], v[34:35], v[74:75], v[56:57] op_sel_hi:[1,0,1]
	v_pk_fma_f32 v[56:57], v[32:33], v[74:75], v[62:63] op_sel_hi:[1,0,1]
	v_mov_b32_e32 v74, v75
	v_pk_fma_f32 v[50:51], v[34:35], v[48:49], v[76:77] op_sel_hi:[1,0,1]
	v_pk_fma_f32 v[48:49], v[32:33], v[48:49], v[80:81] op_sel_hi:[1,0,1]
	v_pk_fma_f32 v[54:55], v[34:35], v[52:53], v[84:85] op_sel_hi:[1,0,1]
	v_pk_fma_f32 v[52:53], v[32:33], v[52:53], v[88:89] op_sel_hi:[1,0,1]
	v_pk_fma_f32 v[62:63], v[34:35], v[74:75], v[60:61] op_sel_hi:[1,0,1]
	v_pk_fma_f32 v[60:61], v[32:33], v[74:75], v[72:73] op_sel_hi:[1,0,1]
	s_waitcnt vmcnt(31)
	v_lshl_add_u64 v[4:5], v[166:167], 0, s[64:65]
	s_waitcnt vmcnt(27)
	v_lshl_add_u64 v[8:9], v[180:181], 0, s[64:65]
	s_waitcnt vmcnt(23)
	v_lshl_add_u64 v[12:13], v[168:169], 0, s[64:65]
	s_waitcnt vmcnt(19)
	v_lshl_add_u64 v[16:17], v[170:171], 0, s[64:65]
	s_waitcnt vmcnt(15)
	v_lshl_add_u64 v[20:21], v[172:173], 0, s[64:65]
	s_waitcnt vmcnt(11)
	v_lshl_add_u64 v[24:25], v[174:175], 0, s[64:65]
	s_waitcnt vmcnt(7)
	v_lshl_add_u64 v[28:29], v[176:177], 0, s[64:65]
	s_waitcnt vmcnt(3)
	v_lshl_add_u64 v[32:33], v[178:179], 0, s[64:65]
	global_load_dwordx4 v[4:7], v[4:5], off nt
	s_nop 0
	global_load_dwordx4 v[8:11], v[8:9], off nt
	s_nop 0
	global_load_dwordx4 v[12:15], v[12:13], off nt
	s_nop 0
	global_load_dwordx4 v[16:19], v[16:17], off nt
	s_nop 0
	global_load_dwordx4 v[20:23], v[20:21], off nt
	s_nop 0
	global_load_dwordx4 v[24:27], v[24:25], off nt
	s_nop 0
	global_load_dwordx4 v[28:31], v[28:29], off nt
	s_nop 0
	global_load_dwordx4 v[32:35], v[32:33], off nt
.LBB0_585:
	s_and_b64 s[100:101], exec, s[36:37]
	s_cbranch_scc0 .Lmod_nowait_1
	s_waitcnt vmcnt(6)
.Lmod_nowait_1:
	v_lshlrev_b32_e32 v82, 16, v142
	v_and_b32_e32 v83, 0xffff0000, v142
	v_lshlrev_b32_e32 v78, 16, v143
	v_and_b32_e32 v79, 0xffff0000, v143
	v_pk_mul_f32 v[84:85], v[38:39], v[78:79]
	v_pk_mul_f32 v[86:87], v[36:37], v[82:83]
	v_pk_mul_f32 v[230:231], v[84:85], v[84:85]
	v_pk_mul_f32 v[232:233], v[86:87], v[86:87]
	s_and_b64 s[100:101], exec, s[36:37]
	s_cbranch_scc0 .Lmod_nowait_2
	s_waitcnt vmcnt(4)
.Lmod_nowait_2:
	v_lshlrev_b32_e32 v90, 16, v146
	v_and_b32_e32 v91, 0xffff0000, v146
	v_lshlrev_b32_e32 v88, 16, v147
	v_and_b32_e32 v89, 0xffff0000, v147
	v_pk_mov_b32 v[234:235], v[232:233], v[230:231] op_sel:[1,0]
	v_mov_b32_e32 v233, v231
	v_pk_add_f32 v[230:231], v[234:235], v[232:233]
	v_pk_mul_f32 v[88:89], v[38:39], v[88:89]
	v_pk_mul_f32 v[90:91], v[36:37], v[90:91]
	v_add_f32_e32 v1, v230, v231
	v_pk_mul_f32 v[230:231], v[88:89], v[88:89]
	v_pk_mul_f32 v[232:233], v[90:91], v[90:91]
	v_lshlrev_b32_e32 v76, 16, v148
	v_pk_mov_b32 v[234:235], v[232:233], v[230:231] op_sel:[1,0]
	v_mov_b32_e32 v233, v231
	v_pk_add_f32 v[230:231], v[234:235], v[232:233]
	v_and_b32_e32 v77, 0xffff0000, v148
	v_add_f32_e32 v135, v230, v231
	v_lshlrev_b32_e32 v80, 16, v149
	v_and_b32_e32 v81, 0xffff0000, v149
	v_add_f32_dpp v1, v1, v1 quad_perm:[1,0,3,2] row_mask:0xf bank_mask:0xf bound_ctrl:1
	v_add_f32_dpp v135, v135, v135 quad_perm:[1,0,3,2] row_mask:0xf bank_mask:0xf bound_ctrl:1
	v_pk_add_f32 v[230:231], v[80:81], -1.0 op_sel_hi:[1,0]
	v_add_f32_dpp v1, v1, v1 quad_perm:[2,3,0,1] row_mask:0xf bank_mask:0xf bound_ctrl:1
	v_add_f32_dpp v135, v135, v135 quad_perm:[2,3,0,1] row_mask:0xf bank_mask:0xf bound_ctrl:1
	v_pk_add_f32 v[232:233], v[76:77], -1.0 op_sel_hi:[1,0]
	v_add_f32_dpp v1, v1, v1 row_half_mirror row_mask:0xf bank_mask:0xf bound_ctrl:1
	v_add_f32_dpp v135, v135, v135 row_half_mirror row_mask:0xf bank_mask:0xf bound_ctrl:1
	v_pk_fma_f32 v[232:233], v[40:41], v[232:233], 1.0 op_sel_hi:[1,1,0]
	v_pk_fma_f32 v[230:231], v[42:43], v[230:231], 1.0 op_sel_hi:[1,1,0]
	v_lshlrev_b32_e32 v72, 16, v140
	v_and_b32_e32 v73, 0xffff0000, v140
	v_lshlrev_b32_e32 v74, 16, v141
	v_and_b32_e32 v75, 0xffff0000, v141
	v_mov_b32_dpp v3, v1 row_mirror row_mask:0xf bank_mask:0xf bound_ctrl:1
	v_mov_b32_dpp v137, v135 row_mirror row_mask:0xf bank_mask:0xf bound_ctrl:1
	v_pk_mul_f32 v[78:79], v[230:231], v[78:79]
	s_and_b64 vcc, exec, s[34:35]
	v_pk_mul_f32 v[82:83], v[232:233], v[82:83]
	s_cbranch_vccnz .LBB0_589
	v_pk_mul_f32 v[230:231], v[78:79], v[74:75]
	v_pk_mul_f32 v[232:233], v[82:83], v[72:73]
	v_mul_f32_e32 v231, v47, v231
	v_mul_f32_e32 v229, v45, v233
	v_fmac_f32_e32 v229, v44, v232
	v_fmac_f32_e32 v231, v46, v230
	v_add_f32_e32 v229, v229, v231
	s_nop 1
	v_add_f32_dpp v229, v229, v229 quad_perm:[1,0,3,2] row_mask:0xf bank_mask:0xf bound_ctrl:1
	s_nop 1
	v_add_f32_dpp v229, v229, v229 quad_perm:[2,3,0,1] row_mask:0xf bank_mask:0xf bound_ctrl:1
	s_nop 1
	v_add_f32_dpp v229, v229, v229 row_half_mirror row_mask:0xf bank_mask:0xf bound_ctrl:1
	s_nop 1
	v_mov_b32_dpp v230, v229 row_mirror row_mask:0xf bank_mask:0xf bound_ctrl:1
	s_and_saveexec_b64 s[8:9], s[12:13]
	s_cbranch_execz .LBB0_588
	v_add_f32_e32 v229, v229, v230
	v_add3_u32 v230, v182, s38, 64
	v_ashrrev_i32_e32 v231, 31, v230
	v_lshlrev_b64 v[230:231], 7, v[230:231]
	v_lshl_add_u64 v[230:231], s[58:59], 0, v[230:231]
	global_store_dword v[230:231], v229, off

.LBB0_593:
	s_or_b64 exec, exec, s[8:9]
	s_and_b64 s[100:101], exec, s[36:37]
	s_cbranch_scc0 .Lmod_nowait_3
	s_waitcnt vmcnt(2)
.Lmod_nowait_3:
	v_lshlrev_b32_e32 v82, 16, v152
	v_and_b32_e32 v83, 0xffff0000, v152
	v_lshlrev_b32_e32 v78, 16, v153
	v_and_b32_e32 v79, 0xffff0000, v153
	v_pk_mul_f32 v[84:85], v[38:39], v[78:79]
	v_pk_mul_f32 v[86:87], v[36:37], v[82:83]
	v_pk_mul_f32 v[230:231], v[84:85], v[84:85]
	v_pk_mul_f32 v[232:233], v[86:87], v[86:87]
	s_and_b64 s[100:101], exec, s[36:37]
	s_cbranch_scc0 .Lmod_nowait_4
	s_waitcnt vmcnt(0)
.Lmod_nowait_4:
	v_lshlrev_b32_e32 v90, 16, v158
	v_and_b32_e32 v91, 0xffff0000, v158
	v_lshlrev_b32_e32 v88, 16, v159
	v_and_b32_e32 v89, 0xffff0000, v159
	v_pk_mov_b32 v[234:235], v[232:233], v[230:231] op_sel:[1,0]
	v_mov_b32_e32 v233, v231
	v_pk_add_f32 v[230:231], v[234:235], v[232:233]
	v_pk_mul_f32 v[88:89], v[38:39], v[88:89]
	v_pk_mul_f32 v[90:91], v[36:37], v[90:91]
	v_add_f32_e32 v135, v230, v231
	v_pk_mul_f32 v[230:231], v[88:89], v[88:89]
	v_pk_mul_f32 v[232:233], v[90:91], v[90:91]
	v_lshlrev_b32_e32 v76, 16, v156
	v_pk_mov_b32 v[234:235], v[232:233], v[230:231] op_sel:[1,0]
	v_mov_b32_e32 v233, v231
	v_pk_add_f32 v[230:231], v[234:235], v[232:233]
	v_and_b32_e32 v77, 0xffff0000, v156
	v_add_f32_e32 v229, v230, v231
	v_lshlrev_b32_e32 v80, 16, v157
	v_and_b32_e32 v81, 0xffff0000, v157
	v_add_f32_dpp v135, v135, v135 quad_perm:[1,0,3,2] row_mask:0xf bank_mask:0xf bound_ctrl:1
	v_add_f32_dpp v229, v229, v229 quad_perm:[1,0,3,2] row_mask:0xf bank_mask:0xf bound_ctrl:1
	v_pk_add_f32 v[232:233], v[80:81], -1.0 op_sel_hi:[1,0]
	v_add_f32_dpp v135, v135, v135 quad_perm:[2,3,0,1] row_mask:0xf bank_mask:0xf bound_ctrl:1
	v_add_f32_dpp v229, v229, v229 quad_perm:[2,3,0,1] row_mask:0xf bank_mask:0xf bound_ctrl:1
	v_pk_add_f32 v[234:235], v[76:77], -1.0 op_sel_hi:[1,0]
	v_add_f32_dpp v135, v135, v135 row_half_mirror row_mask:0xf bank_mask:0xf bound_ctrl:1
	v_add_f32_dpp v229, v229, v229 row_half_mirror row_mask:0xf bank_mask:0xf bound_ctrl:1
	v_pk_fma_f32 v[234:235], v[40:41], v[234:235], 1.0 op_sel_hi:[1,1,0]
	v_pk_fma_f32 v[232:233], v[42:43], v[232:233], 1.0 op_sel_hi:[1,1,0]
	v_lshlrev_b32_e32 v72, 16, v150
	v_and_b32_e32 v73, 0xffff0000, v150
	v_lshlrev_b32_e32 v74, 16, v151
	v_and_b32_e32 v75, 0xffff0000, v151
	v_mov_b32_dpp v137, v135 row_mirror row_mask:0xf bank_mask:0xf bound_ctrl:1
	v_mov_b32_dpp v230, v229 row_mirror row_mask:0xf bank_mask:0xf bound_ctrl:1
	v_pk_mul_f32 v[78:79], v[232:233], v[78:79]
	s_and_b64 vcc, exec, s[34:35]
	v_pk_mul_f32 v[82:83], v[234:235], v[82:83]
	s_cbranch_vccnz .LBB0_597
	v_pk_mul_f32 v[232:233], v[78:79], v[74:75]
	v_pk_mul_f32 v[234:235], v[82:83], v[72:73]
	v_mul_f32_e32 v233, v47, v233
	v_mul_f32_e32 v231, v45, v235
	v_fmac_f32_e32 v231, v44, v234
	v_fmac_f32_e32 v233, v46, v232
	v_add_f32_e32 v231, v231, v233
	s_nop 1
	v_add_f32_dpp v231, v231, v231 quad_perm:[1,0,3,2] row_mask:0xf bank_mask:0xf bound_ctrl:1
	s_nop 1
	v_add_f32_dpp v231, v231, v231 quad_perm:[2,3,0,1] row_mask:0xf bank_mask:0xf bound_ctrl:1
	s_nop 1
	v_add_f32_dpp v231, v231, v231 row_half_mirror row_mask:0xf bank_mask:0xf bound_ctrl:1
	s_nop 1
	v_mov_b32_dpp v232, v231 row_mirror row_mask:0xf bank_mask:0xf bound_ctrl:1
	s_and_saveexec_b64 s[8:9], s[12:13]
	s_cbranch_execz .LBB0_596
	v_add_f32_e32 v231, v231, v232
	v_add_u32_e32 v232, s38, v182
	v_add_u32_e32 v232, 0x50, v232
	v_ashrrev_i32_e32 v233, 31, v232
	v_lshlrev_b64 v[232:233], 7, v[232:233]
	v_lshl_add_u64 v[232:233], s[58:59], 0, v[232:233]
	global_store_dword v[232:233], v231, off

.LBB0_621:
	s_and_b32 s6, s56, 0x400
	v_lshl_add_u32 v1, s6, 2, v191
	ds_read_b128 v[72:75], v1
	v_add_u32_e32 v76, s38, v164
	v_ashrrev_i32_e32 v77, 31, v76
	v_lshlrev_b64 v[76:77], 13, v[76:77]
	v_lshl_add_u64 v[76:77], v[138:139], 0, v[76:77]
	s_andn2_b64 vcc, exec, s[8:9]
	s_waitcnt lgkmcnt(0)
	global_store_dwordx4 v[76:77], v[72:75], off
	s_cbranch_vccnz .LBB0_623
	v_ashrrev_i32_e32 v1, 31, v218
	v_lshrrev_b32_e32 v1, 27, v1
	v_add_u32_e32 v1, v218, v1
	v_ashrrev_i32_e32 v1, 5, v1
	v_sub_u32_e32 v3, 0, v1
	v_max_i32_e32 v3, v1, v3
	v_cvt_f32_u32_e32 v72, v3
	v_sub_u32_e32 v75, 0, v3
	v_sub_u32_e32 v73, 0, v217
	v_max_i32_e32 v73, v217, v73
	v_rcp_iflag_f32_e32 v72, v72
	v_xor_b32_e32 v74, v217, v1
	s_waitcnt vmcnt(31)
	ds_write2_b32 v223, v4, v5 offset1:66
	s_waitcnt vmcnt(29)
	ds_write2_b32 v223, v6, v7 offset0:132 offset1:198
	s_waitcnt vmcnt(27)
	ds_write2_b32 v228, v8, v9 offset0:8 offset1:74
	s_waitcnt vmcnt(25)
	ds_write2_b32 v228, v10, v11 offset0:140 offset1:206
	s_waitcnt vmcnt(23)
	ds_write2_b32 v227, v12, v13 offset0:16 offset1:82
	s_waitcnt vmcnt(21)
	ds_write2_b32 v227, v14, v15 offset0:148 offset1:214
	s_waitcnt vmcnt(19)
	ds_write2_b32 v226, v16, v17 offset0:24 offset1:90
	s_waitcnt vmcnt(17)
	ds_write2_b32 v226, v18, v19 offset0:156 offset1:222
	s_waitcnt vmcnt(15)
	ds_write2_b32 v225, v20, v21 offset0:32 offset1:98
	s_waitcnt vmcnt(13)
	ds_write2_b32 v225, v22, v23 offset0:164 offset1:230
	s_waitcnt vmcnt(11)
	ds_write2_b32 v224, v24, v25 offset0:40 offset1:106
	s_waitcnt vmcnt(9)
	ds_write2_b32 v224, v26, v27 offset0:172 offset1:238
	s_waitcnt vmcnt(7)
	ds_write2_b32 v222, v28, v29 offset0:48 offset1:114
	s_waitcnt vmcnt(5)
	ds_write2_b32 v222, v30, v31 offset0:180 offset1:246
	s_waitcnt vmcnt(3)
	ds_write2_b32 v221, v32, v33 offset0:56 offset1:122
	s_waitcnt vmcnt(1)
	ds_write2_b32 v221, v34, v35 offset0:188 offset1:254
	v_ashrrev_i32_e32 v74, 31, v74
	v_mul_f32_e32 v72, 0x4f7ffffe, v72
	v_cvt_u32_f32_e32 v72, v72
	s_waitcnt lgkmcnt(0)
	ds_read2_b32 v[80:81], v220 offset0:33 offset1:41
	ds_read2_b32 v[82:83], v220 offset0:66 offset1:74
	v_mul_lo_u32 v75, v75, v72
	v_mul_hi_u32 v75, v72, v75
	v_add_u32_e32 v72, v72, v75
	v_mul_hi_u32 v72, v73, v72
	v_mul_lo_u32 v75, v72, v3
	v_sub_u32_e32 v73, v73, v75
	v_add_u32_e32 v76, 1, v72
	v_cmp_ge_u32_e32 vcc, v73, v3
	v_sub_u32_e32 v75, v73, v3
	ds_read2_b32 v[84:85], v220 offset0:99 offset1:107
	v_cndmask_b32_e32 v72, v72, v76, vcc
	v_cndmask_b32_e32 v73, v73, v75, vcc
	v_add_u32_e32 v75, 1, v72
	v_cmp_ge_u32_e32 vcc, v73, v3
	ds_read2_b32 v[76:77], v220 offset1:8
	ds_read2_b32 v[86:87], v220 offset0:132 offset1:140
	v_cndmask_b32_e32 v3, v72, v75, vcc
	v_xor_b32_e32 v3, v3, v74
	v_sub_u32_e32 v3, v3, v74
	v_lshlrev_b32_e32 v72, 6, v3
	v_ashrrev_i32_e32 v73, 31, v72
	v_mul_lo_u32 v1, v3, v1
	v_lshl_add_u64 v[72:73], v[72:73], 1, v[132:133]
	v_mov_b32_e32 v3, v0
	v_lshl_add_u64 v[78:79], v[72:73], 0, v[2:3]
	s_waitcnt lgkmcnt(1)
	ds_read2_b32 v[88:89], v220 offset0:165 offset1:173
	v_cvt_pk_bf16_f32 v72, v76, v80
	ds_read2_b32 v[90:91], v220 offset0:198 offset1:206
	ds_read2_b32 v[230:231], v220 offset0:231 offset1:239
	v_cvt_pk_bf16_f32 v73, v82, v84
	s_waitcnt lgkmcnt(3)
	s_waitcnt lgkmcnt(2)
	v_cvt_pk_bf16_f32 v74, v86, v88
	s_waitcnt lgkmcnt(1)
	v_sub_u32_e32 v1, v217, v1
	s_waitcnt lgkmcnt(0)
	v_lshlrev_b32_e32 v1, 5, v1
	v_cvt_pk_bf16_f32 v75, v90, v230
	v_or_b32_e32 v3, v1, v192
	v_mad_i64_i32 v[232:233], s[6:7], v3, v219, 0
	v_lshl_add_u64 v[232:233], v[232:233], 1, v[78:79]
	global_store_dwordx4 v[232:233], v[72:75], off
	s_nop 1
	v_cvt_pk_bf16_f32 v72, v77, v81
	v_cvt_pk_bf16_f32 v73, v83, v85
	v_cvt_pk_bf16_f32 v74, v87, v89
	v_cvt_pk_bf16_f32 v75, v91, v231
	v_or_b32_e32 v3, v1, v199
	v_mad_i64_i32 v[80:81], s[6:7], v3, v219, 0
	ds_read2_b32 v[76:77], v220 offset0:16 offset1:24
	v_lshl_add_u64 v[80:81], v[80:81], 1, v[78:79]
	global_store_dwordx4 v[80:81], v[72:75], off
	ds_read2_b32 v[80:81], v220 offset0:49 offset1:57
	ds_read2_b32 v[82:83], v220 offset0:82 offset1:90
	ds_read2_b32 v[84:85], v220 offset0:115 offset1:123
	s_waitcnt lgkmcnt(3)
	s_waitcnt lgkmcnt(2)
	ds_read2_b32 v[86:87], v220 offset0:148 offset1:156
	ds_read2_b32 v[88:89], v220 offset0:181 offset1:189
	v_cvt_pk_bf16_f32 v72, v76, v80
	s_waitcnt lgkmcnt(3)
	s_waitcnt lgkmcnt(2)
	ds_read2_b32 v[90:91], v220 offset0:214 offset1:222
	ds_read2_b32 v[230:231], v220 offset0:247 offset1:255
	v_cvt_pk_bf16_f32 v73, v82, v84
	s_waitcnt lgkmcnt(3)
	s_waitcnt lgkmcnt(2)
	v_cvt_pk_bf16_f32 v74, v86, v88
	s_waitcnt lgkmcnt(1)
	s_waitcnt lgkmcnt(0)
	v_cvt_pk_bf16_f32 v75, v90, v230
	v_or_b32_e32 v3, v1, v200
	v_mad_i64_i32 v[232:233], s[6:7], v3, v219, 0
	v_lshl_add_u64 v[232:233], v[232:233], 1, v[78:79]
	global_store_dwordx4 v[232:233], v[72:75], off
	s_nop 1
	v_cvt_pk_bf16_f32 v72, v77, v81
	v_cvt_pk_bf16_f32 v73, v83, v85
	v_cvt_pk_bf16_f32 v74, v87, v89
	v_or_b32_e32 v1, v1, v201
	v_mad_i64_i32 v[76:77], s[6:7], v1, v219, 0
	v_cvt_pk_bf16_f32 v75, v91, v231
	v_lshl_add_u64 v[76:77], v[76:77], 1, v[78:79]
	global_store_dwordx4 v[76:77], v[72:75], off
	s_waitcnt lgkmcnt(0)
.LBB0_623:
	s_branch .LBB0_582
.LBB0_625:
	s_or_b64 exec, exec, s[8:9]
	s_and_saveexec_b64 s[8:9], s[12:13]
	s_cbranch_execz .LBB0_591

	.amdhsa_kernel _Z14fwd_megakernel4Args
		.amdhsa_group_segment_fixed_size 0
		.amdhsa_private_segment_fixed_size 0
		.amdhsa_kernarg_size 552
		.amdhsa_user_sgpr_count 2
		.amdhsa_user_sgpr_dispatch_ptr 0
		.amdhsa_user_sgpr_queue_ptr 0
		.amdhsa_user_sgpr_kernarg_segment_ptr 1
		.amdhsa_user_sgpr_dispatch_id 0
		.amdhsa_user_sgpr_kernarg_preload_length 0
		.amdhsa_user_sgpr_kernarg_preload_offset 0
		.amdhsa_user_sgpr_private_segment_size 0
		.amdhsa_uses_dynamic_stack 0
		.amdhsa_enable_private_segment 0
		.amdhsa_system_sgpr_workgroup_id_x 1
		.amdhsa_system_sgpr_workgroup_id_y 0
		.amdhsa_system_sgpr_workgroup_id_z 0
		.amdhsa_system_sgpr_workgroup_info 0
		.amdhsa_system_vgpr_workitem_id 2
		.amdhsa_next_free_vgpr 252
		.amdhsa_next_free_sgpr 102
		.amdhsa_accum_offset 252
		.amdhsa_reserve_vcc 1
		.amdhsa_float_round_mode_32 0
		.amdhsa_float_round_mode_16_64 0
		.amdhsa_float_denorm_mode_32 3
		.amdhsa_float_denorm_mode_16_64 3
		.amdhsa_dx10_clamp 1
		.amdhsa_ieee_mode 1
		.amdhsa_fp16_overflow 0
		.amdhsa_tg_split 0
		.amdhsa_exception_fp_ieee_invalid_op 0
		.amdhsa_exception_fp_denorm_src 0
		.amdhsa_exception_fp_ieee_div_zero 0
		.amdhsa_exception_fp_ieee_overflow 0
		.amdhsa_exception_fp_ieee_underflow 0
		.amdhsa_exception_fp_ieee_inexact 0
		.amdhsa_exception_int_div_zero 0
	.end_amdhsa_kernel

amdhsa.kernels:
  - .agpr_count:     0
    .args:
      - .offset:         0
        .size:           296
        .value_kind:     by_value
      - .offset:         296
        .size:           4
        .value_kind:     hidden_block_count_x
      - .offset:         300
        .size:           4
        .value_kind:     hidden_block_count_y
      - .offset:         304
        .size:           4
        .value_kind:     hidden_block_count_z
      - .offset:         308
        .size:           2
        .value_kind:     hidden_group_size_x
      - .offset:         310
        .size:           2
        .value_kind:     hidden_group_size_y
      - .offset:         312
        .size:           2
        .value_kind:     hidden_group_size_z
      - .offset:         314
        .size:           2
        .value_kind:     hidden_remainder_x
      - .offset:         316
        .size:           2
        .value_kind:     hidden_remainder_y
      - .offset:         318
        .size:           2
        .value_kind:     hidden_remainder_z
      - .offset:         336
        .size:           8
        .value_kind:     hidden_global_offset_x
      - .offset:         344
        .size:           8
        .value_kind:     hidden_global_offset_y
      - .offset:         352
        .size:           8
        .value_kind:     hidden_global_offset_z
      - .offset:         360
        .size:           2
        .value_kind:     hidden_grid_dims
      - .offset:         384
        .size:           8
        .value_kind:     hidden_multigrid_sync_arg
      - .offset:         416
        .size:           4
        .value_kind:     hidden_dynamic_lds_size
    .group_segment_fixed_size: 0
    .kernarg_segment_align: 8
    .kernarg_segment_size: 552
    .language:       OpenCL C
    .language_version:
      - 2
      - 0
    .max_flat_workgroup_size: 512
    .name:           _Z14fwd_megakernel4Args
    .private_segment_fixed_size: 0
    .sgpr_count:     108
    .sgpr_spill_count: 156
    .symbol:         _Z14fwd_megakernel4Args.kd
    .uniform_work_group_size: 1
    .uses_dynamic_stack: false
    .vgpr_count:     252
    .vgpr_spill_count: 0
    .wavefront_size: 64
